# speedup vs baseline: 1.0162x; 1.0081x over previous
; #define LAS __attribute__((address_space(3)))
; __device__ __forceinline__ unsigned pk2n(float lo, float hi) { const f32x2 v = {lo, hi}; const bf16x2n b = __builtin_convertvector(v, bf16x2n); return __builtin_bit_cast(unsigned, b); }
; __device__ __forceinline__ float bflo(unsigned w) { return __uint_as_float(w << 16); }
; __device__ __forceinline__ float bfhi(unsigned w) { return __uint_as_float(w & 0xffff0000u); }
; #define CFENCE() asm volatile("" ::: "memory")
; #define DS_GUARD() do { __builtin_amdgcn_sched_barrier(0); asm volatile("s_waitcnt lgkmcnt(0)" ::: "memory"); __builtin_amdgcn_sched_barrier(0); } while (0)
; template <bool OUT> ...
;     ...
;         u32x2 bwp[2][8];
; #pragma unroll
;         for (int mt = 0; mt < 2; ++mt)
; #pragma unroll
;             for (int nt = 0; nt < 8; ++nt) {
;                 const f32x4 bu = __builtin_amdgcn_mfma_f32_16x16x32_bf16(bfrag[nt], ua[mt], (f32x4){0.f, 0.f, 0.f, 0.f}, 0, 0, 0);
;                 bwp[mt][nt].x = pk2n(bu.x, bu.y); bwp[mt][nt].y = pk2n(bu.z, bu.w);
;             }
;         __builtin_amdgcn_sched_barrier(0);
; #pragma unroll
;         for (int mt = 0; mt < 2; ++mt)
; #pragma unroll
;             for (int nt = 0; nt < 8; ++nt) *(LAS u32x2*)(wl + (16 * mt + fr) * 68 + 8 * nt + 2 * fq) = bwp[mt][nt];
;         DS_GUARD();
;         CFENCE();
;         {
;             f32x2 hv = {hr, hi}; const f32x2 L1 = {lr, lr}, L2 = {-li, li};
;             unsigned cur8[8], nxt8[8], hw8[8];
; #pragma unroll
;             for (int j = 0; j < 8; ++j) cur8[j] = wl[j * 68 + lane];
; #pragma unroll
;             for (int blk = 0; blk < 4; ++blk) {
;                 if (blk < 3) {
; #pragma unroll
;                     for (int j = 0; j < 8; ++j) nxt8[j] = wl[(8 * (blk + 1) + j) * 68 + lane];
;                 }
; #pragma unroll
;                 for (int j = 0; j < 8; ++j) {
;                     const unsigned bw = cur8[j];
;                     const f32x2 bv = {bflo(bw), bfhi(bw)};
;                     const f32x2 hs = __builtin_shufflevector(hv, hv, 1, 0);
;                     hv = __builtin_elementwise_fma(L1, hv, __builtin_elementwise_fma(L2, hs, bv));
.LBB0_660:
	s_or_b64 exec, exec, s[12:13]
	s_waitcnt lgkmcnt(0)
	v_mfma_f32_16x16x32_bf16 v[146:149], v[6:9], v[58:61], 0
	v_mfma_f32_16x16x32_bf16 v[150:153], v[14:17], v[58:61], 0
	v_mfma_f32_16x16x32_bf16 v[154:157], v[2:5], v[58:61], 0
	v_mfma_f32_16x16x32_bf16 v[158:161], v[10:13], v[58:61], 0
	v_mfma_f32_16x16x32_bf16 v[162:165], v[18:21], v[58:61], 0
	v_mfma_f32_16x16x32_bf16 v[166:169], v[22:25], v[58:61], 0
	v_mfma_f32_16x16x32_bf16 v[170:173], v[26:29], v[58:61], 0
	v_mfma_f32_16x16x32_bf16 v[174:177], v[30:33], v[58:61], 0
	v_mfma_f32_16x16x32_bf16 v[178:181], v[6:9], v[54:57], 0
	v_mfma_f32_16x16x32_bf16 v[182:185], v[2:5], v[54:57], 0
	v_mfma_f32_16x16x32_bf16 v[186:189], v[10:13], v[54:57], 0
	v_mfma_f32_16x16x32_bf16 v[190:193], v[14:17], v[54:57], 0
	v_mfma_f32_16x16x32_bf16 v[194:197], v[18:21], v[54:57], 0
	v_mfma_f32_16x16x32_bf16 v[198:201], v[22:25], v[54:57], 0
	v_mfma_f32_16x16x32_bf16 v[202:205], v[26:29], v[54:57], 0
	v_mfma_f32_16x16x32_bf16 v[206:209], v[30:33], v[54:57], 0
	v_cvt_pk_bf16_f32 v70, v146, v147
	v_cvt_pk_bf16_f32 v71, v148, v149
	v_cvt_pk_bf16_f32 v72, v154, v155
	v_cvt_pk_bf16_f32 v73, v156, v157
	v_cvt_pk_bf16_f32 v74, v158, v159
	v_cvt_pk_bf16_f32 v75, v160, v161
	v_cvt_pk_bf16_f32 v76, v150, v151
	v_cvt_pk_bf16_f32 v77, v152, v153
	v_cvt_pk_bf16_f32 v90, v162, v163
	v_cvt_pk_bf16_f32 v91, v164, v165
	v_cvt_pk_bf16_f32 v92, v166, v167
	v_cvt_pk_bf16_f32 v93, v168, v169
	v_cvt_pk_bf16_f32 v86, v170, v171
	v_cvt_pk_bf16_f32 v87, v172, v173
	v_cvt_pk_bf16_f32 v88, v174, v175
	v_cvt_pk_bf16_f32 v89, v176, v177
	v_cvt_pk_bf16_f32 v94, v178, v179
	v_cvt_pk_bf16_f32 v95, v180, v181
	v_cvt_pk_bf16_f32 v96, v182, v183
	v_cvt_pk_bf16_f32 v97, v184, v185
	v_cvt_pk_bf16_f32 v98, v186, v187
	v_cvt_pk_bf16_f32 v99, v188, v189
	v_cvt_pk_bf16_f32 v100, v190, v191
	v_cvt_pk_bf16_f32 v101, v192, v193
	v_cvt_pk_bf16_f32 v102, v194, v195
	v_cvt_pk_bf16_f32 v103, v196, v197
	v_cvt_pk_bf16_f32 v104, v198, v199
	v_cvt_pk_bf16_f32 v105, v200, v201
	v_cvt_pk_bf16_f32 v58, v202, v203
	v_cvt_pk_bf16_f32 v59, v204, v205
	v_cvt_pk_bf16_f32 v54, v206, v207
	v_cvt_pk_bf16_f32 v55, v208, v209
	ds_write2_b64 v85, v[70:71], v[72:73] offset1:4
	ds_write2_b64 v85, v[74:75], v[76:77] offset0:8 offset1:12
	ds_write2_b64 v85, v[90:91], v[92:93] offset0:16 offset1:20
	ds_write2_b64 v85, v[86:87], v[88:89] offset0:24 offset1:28
	v_add_u32_e32 v86, 0x1000, v85
	ds_write2_b64 v86, v[94:95], v[96:97] offset0:32 offset1:36
	ds_write2_b64 v86, v[98:99], v[100:101] offset0:40 offset1:44
	ds_write2_b64 v86, v[102:103], v[104:105] offset0:48 offset1:52
	ds_write2_b64 v86, v[58:59], v[54:55] offset0:56 offset1:60
	s_waitcnt lgkmcnt(0)
	ds_read2_b32 v[54:55], v83 offset1:68
	ds_read2_b32 v[56:57], v83 offset0:136 offset1:204
	v_add_u32_e32 v87, 0x400, v83
	ds_read2_b32 v[58:59], v87 offset0:16 offset1:84
	ds_read2_b32 v[60:61], v87 offset0:152 offset1:220
	v_add_u32_e32 v88, 0x800, v83
	s_waitcnt lgkmcnt(3)
	v_lshlrev_b32_e32 v90, 16, v54
	v_and_b32_e32 v91, 0xffff0000, v54
	v_pk_fma_f32 v[90:91], v[66:67], v[68:69], v[90:91] op_sel:[0,1,0] op_sel_hi:[1,0,1]
	v_lshlrev_b32_e32 v54, 16, v55
	v_pk_fma_f32 v[68:69], v[64:65], v[68:69], v[90:91]
	v_and_b32_e32 v55, 0xffff0000, v55
	v_pk_fma_f32 v[54:55], v[66:67], v[68:69], v[54:55] op_sel:[0,1,0] op_sel_hi:[1,0,1]
	ds_read2_b32 v[70:71], v88 offset0:32 offset1:100
	ds_read2_b32 v[72:73], v88 offset0:168 offset1:236
	v_pk_fma_f32 v[54:55], v[64:65], v[68:69], v[54:55]
	s_waitcnt lgkmcnt(4)
	v_lshlrev_b32_e32 v68, 16, v56
	v_and_b32_e32 v69, 0xffff0000, v56
	v_pk_fma_f32 v[68:69], v[66:67], v[54:55], v[68:69] op_sel:[0,1,0] op_sel_hi:[1,0,1]
	v_lshlrev_b32_e32 v56, 16, v57
	v_pk_fma_f32 v[54:55], v[64:65], v[54:55], v[68:69]
	v_and_b32_e32 v57, 0xffff0000, v57
	v_pk_fma_f32 v[56:57], v[66:67], v[54:55], v[56:57] op_sel:[0,1,0] op_sel_hi:[1,0,1]
	s_waitcnt lgkmcnt(1)
	v_lshlrev_b32_e32 v94, 16, v70
	v_pk_fma_f32 v[54:55], v[64:65], v[54:55], v[56:57]
	v_lshlrev_b32_e32 v56, 16, v58
	v_and_b32_e32 v57, 0xffff0000, v58
	v_pk_fma_f32 v[56:57], v[66:67], v[54:55], v[56:57] op_sel:[0,1,0] op_sel_hi:[1,0,1]
	v_and_b32_e32 v95, 0xffff0000, v70
	v_pk_fma_f32 v[54:55], v[64:65], v[54:55], v[56:57]
	v_lshlrev_b32_e32 v56, 16, v59
	v_and_b32_e32 v57, 0xffff0000, v59
	v_pk_fma_f32 v[56:57], v[66:67], v[54:55], v[56:57] op_sel:[0,1,0] op_sel_hi:[1,0,1]
	v_lshlrev_b32_e32 v70, 16, v71
	v_pk_fma_f32 v[54:55], v[64:65], v[54:55], v[56:57]
	v_lshlrev_b32_e32 v56, 16, v60
	v_and_b32_e32 v57, 0xffff0000, v60
	v_pk_fma_f32 v[56:57], v[66:67], v[54:55], v[56:57] op_sel:[0,1,0] op_sel_hi:[1,0,1]
	v_and_b32_e32 v71, 0xffff0000, v71
	v_pk_fma_f32 v[54:55], v[64:65], v[54:55], v[56:57]
	v_lshlrev_b32_e32 v56, 16, v61
	v_and_b32_e32 v57, 0xffff0000, v61
	v_pk_fma_f32 v[56:57], v[66:67], v[54:55], v[56:57] op_sel:[0,1,0] op_sel_hi:[1,0,1]
	v_add_u32_e32 v89, 0xc00, v83
	v_pk_fma_f32 v[54:55], v[64:65], v[54:55], v[56:57]
	ds_read2_b32 v[74:75], v89 offset0:48 offset1:116
	ds_read2_b32 v[76:77], v89 offset0:184 offset1:252
	v_pk_fma_f32 v[94:95], v[66:67], v[54:55], v[94:95] op_sel:[0,1,0] op_sel_hi:[1,0,1]
	v_add_u32_e32 v90, 0x1000, v83
	v_pk_fma_f32 v[54:55], v[64:65], v[54:55], v[94:95]
	ds_read2_b32 v[56:57], v90 offset0:64 offset1:132
	v_pk_fma_f32 v[70:71], v[66:67], v[54:55], v[70:71] op_sel:[0,1,0] op_sel_hi:[1,0,1]
	v_add_u32_e32 v91, 0x1200, v83
	v_pk_fma_f32 v[54:55], v[64:65], v[54:55], v[70:71]
	s_waitcnt lgkmcnt(3)
; __device__ __forceinline__ unsigned pk2n(float lo, float hi) { const f32x2 v = {lo, hi}; const bf16x2n b = __builtin_convertvector(v, bf16x2n); return __builtin_bit_cast(unsigned, b); }
; __device__ __forceinline__ float bflo(unsigned w) { return __uint_as_float(w << 16); }
; __device__ __forceinline__ float bfhi(unsigned w) { return __uint_as_float(w & 0xffff0000u); }
; #define DS_GUARD() do { __builtin_amdgcn_sched_barrier(0); asm volatile("s_waitcnt lgkmcnt(0)" ::: "memory"); __builtin_amdgcn_sched_barrier(0); } while (0)
; template <bool OUT> ...
;     ...
; #pragma unroll
;             for (int j = 0; j < 8; ++j) cur8[j] = wl[j * 68 + lane];
; #pragma unroll
;             for (int blk = 0; blk < 4; ++blk) {
;                 if (blk < 3) {
; #pragma unroll
;                     for (int j = 0; j < 8; ++j) nxt8[j] = wl[(8 * (blk + 1) + j) * 68 + lane];
;                 }
; #pragma unroll
;                 for (int j = 0; j < 8; ++j) {
;                     const unsigned bw = cur8[j];
;                     const f32x2 bv = {bflo(bw), bfhi(bw)};
;                     const f32x2 hs = __builtin_shufflevector(hv, hv, 1, 0);
;                     hv = __builtin_elementwise_fma(L1, hv, __builtin_elementwise_fma(L2, hs, bv));
;                     if (OUT) hw8[j] = pk2n(hv.x, hv.y);
;                 }
;                 if (OUT) {
;                     __builtin_amdgcn_sched_barrier(0);
; #pragma unroll
;                     for (int j = 0; j < 8; ++j) wl[(8 * blk + j) * 68 + lane] = hw8[j];
;                     DS_GUARD();
;                 }
; #pragma unroll
;                 for (int j = 0; j < 8; ++j) cur8[j] = nxt8[j];
;             }
	v_lshlrev_b32_e32 v70, 16, v72
	v_and_b32_e32 v71, 0xffff0000, v72
	v_pk_fma_f32 v[70:71], v[66:67], v[54:55], v[70:71] op_sel:[0,1,0] op_sel_hi:[1,0,1]
	ds_read2_b32 v[58:59], v91 offset0:72 offset1:140
	v_pk_fma_f32 v[54:55], v[64:65], v[54:55], v[70:71]
	v_lshlrev_b32_e32 v70, 16, v73
	v_and_b32_e32 v71, 0xffff0000, v73
	v_pk_fma_f32 v[70:71], v[66:67], v[54:55], v[70:71] op_sel:[0,1,0] op_sel_hi:[1,0,1]
	v_add_u32_e32 v92, 0x1400, v83
	v_pk_fma_f32 v[54:55], v[64:65], v[54:55], v[70:71]
	s_waitcnt lgkmcnt(3)
	v_lshlrev_b32_e32 v70, 16, v74
	v_and_b32_e32 v71, 0xffff0000, v74
	v_pk_fma_f32 v[70:71], v[66:67], v[54:55], v[70:71] op_sel:[0,1,0] op_sel_hi:[1,0,1]
	ds_read2_b32 v[60:61], v92 offset0:80 offset1:148
	v_pk_fma_f32 v[54:55], v[64:65], v[54:55], v[70:71]
	v_lshlrev_b32_e32 v70, 16, v75
	v_and_b32_e32 v71, 0xffff0000, v75
	v_pk_fma_f32 v[70:71], v[66:67], v[54:55], v[70:71] op_sel:[0,1,0] op_sel_hi:[1,0,1]
	v_add_u32_e32 v93, 0x1600, v83
	v_pk_fma_f32 v[54:55], v[64:65], v[54:55], v[70:71]
	s_waitcnt lgkmcnt(3)
	v_lshlrev_b32_e32 v70, 16, v76
	v_and_b32_e32 v71, 0xffff0000, v76
	v_pk_fma_f32 v[70:71], v[66:67], v[54:55], v[70:71] op_sel:[0,1,0] op_sel_hi:[1,0,1]
	ds_read2_b32 v[68:69], v93 offset0:88 offset1:156
	v_pk_fma_f32 v[54:55], v[64:65], v[54:55], v[70:71]
	v_lshlrev_b32_e32 v70, 16, v77
	v_and_b32_e32 v71, 0xffff0000, v77
	v_pk_fma_f32 v[70:71], v[66:67], v[54:55], v[70:71] op_sel:[0,1,0] op_sel_hi:[1,0,1]
	v_add_u32_e32 v95, 0x1800, v83
	v_pk_fma_f32 v[54:55], v[64:65], v[54:55], v[70:71]
	s_waitcnt lgkmcnt(3)
	v_lshlrev_b32_e32 v70, 16, v56
	v_and_b32_e32 v71, 0xffff0000, v56
	v_pk_fma_f32 v[70:71], v[66:67], v[54:55], v[70:71] op_sel:[0,1,0] op_sel_hi:[1,0,1]
	v_lshlrev_b32_e32 v56, 16, v57
	v_pk_fma_f32 v[54:55], v[64:65], v[54:55], v[70:71]
	v_and_b32_e32 v57, 0xffff0000, v57
	v_pk_fma_f32 v[56:57], v[66:67], v[54:55], v[56:57] op_sel:[0,1,0] op_sel_hi:[1,0,1]
	v_add_u32_e32 v97, 0x1a00, v83
	v_pk_fma_f32 v[54:55], v[64:65], v[54:55], v[56:57]
	s_waitcnt lgkmcnt(2)
	v_lshlrev_b32_e32 v56, 16, v58
	v_and_b32_e32 v57, 0xffff0000, v58
	v_pk_fma_f32 v[56:57], v[66:67], v[54:55], v[56:57] op_sel:[0,1,0] op_sel_hi:[1,0,1]
	v_add_u32_e32 v96, 0x1c00, v83
	v_pk_fma_f32 v[54:55], v[64:65], v[54:55], v[56:57]
	v_lshlrev_b32_e32 v56, 16, v59
	v_and_b32_e32 v57, 0xffff0000, v59
	v_pk_fma_f32 v[56:57], v[66:67], v[54:55], v[56:57] op_sel:[0,1,0] op_sel_hi:[1,0,1]
	ds_read2_b32 v[58:59], v95 offset0:96 offset1:164
	v_pk_fma_f32 v[54:55], v[64:65], v[54:55], v[56:57]
	s_waitcnt lgkmcnt(2)
	v_lshlrev_b32_e32 v56, 16, v60
	v_and_b32_e32 v57, 0xffff0000, v60
	v_pk_fma_f32 v[56:57], v[66:67], v[54:55], v[56:57] op_sel:[0,1,0] op_sel_hi:[1,0,1]
	s_waitcnt lgkmcnt(0)
	v_lshlrev_b32_e32 v70, 16, v58
	v_pk_fma_f32 v[54:55], v[64:65], v[54:55], v[56:57]
	v_lshlrev_b32_e32 v56, 16, v61
	v_and_b32_e32 v57, 0xffff0000, v61
	v_pk_fma_f32 v[56:57], v[66:67], v[54:55], v[56:57] op_sel:[0,1,0] op_sel_hi:[1,0,1]
	v_and_b32_e32 v71, 0xffff0000, v58
	v_pk_fma_f32 v[54:55], v[64:65], v[54:55], v[56:57]
	v_lshlrev_b32_e32 v56, 16, v68
	v_and_b32_e32 v57, 0xffff0000, v68
	v_pk_fma_f32 v[56:57], v[66:67], v[54:55], v[56:57] op_sel:[0,1,0] op_sel_hi:[1,0,1]
	v_lshlrev_b32_e32 v58, 16, v59
	v_pk_fma_f32 v[54:55], v[64:65], v[54:55], v[56:57]
	v_lshlrev_b32_e32 v56, 16, v69
	v_and_b32_e32 v57, 0xffff0000, v69
	v_pk_fma_f32 v[56:57], v[66:67], v[54:55], v[56:57] op_sel:[0,1,0] op_sel_hi:[1,0,1]
	ds_read2_b32 v[68:69], v97 offset0:104 offset1:172
	v_pk_fma_f32 v[54:55], v[64:65], v[54:55], v[56:57]
	v_and_b32_e32 v59, 0xffff0000, v59
	v_pk_fma_f32 v[70:71], v[66:67], v[54:55], v[70:71] op_sel:[0,1,0] op_sel_hi:[1,0,1]
	ds_read2_b32 v[60:61], v96 offset0:112 offset1:180
	v_pk_fma_f32 v[54:55], v[64:65], v[54:55], v[70:71]
	v_add_u32_e32 v94, 0x1e00, v83
	v_pk_fma_f32 v[58:59], v[66:67], v[54:55], v[58:59] op_sel:[0,1,0] op_sel_hi:[1,0,1]
	ds_read2_b32 v[56:57], v94 offset0:120 offset1:188
	v_pk_fma_f32 v[54:55], v[64:65], v[54:55], v[58:59]
	s_waitcnt lgkmcnt(2)
	v_lshlrev_b32_e32 v58, 16, v68
	v_and_b32_e32 v59, 0xffff0000, v68
	v_pk_fma_f32 v[58:59], v[66:67], v[54:55], v[58:59] op_sel:[0,1,0] op_sel_hi:[1,0,1]
	s_addk_i32 s24, 0x400
	v_pk_fma_f32 v[54:55], v[64:65], v[54:55], v[58:59]
	v_lshlrev_b32_e32 v58, 16, v69
	v_and_b32_e32 v59, 0xffff0000, v69
	v_pk_fma_f32 v[58:59], v[66:67], v[54:55], v[58:59] op_sel:[0,1,0] op_sel_hi:[1,0,1]
	s_cmpk_lg_i32 s24, 0x2000
	v_pk_fma_f32 v[54:55], v[64:65], v[54:55], v[58:59]
	s_waitcnt lgkmcnt(1)
	v_lshlrev_b32_e32 v58, 16, v60
	v_and_b32_e32 v59, 0xffff0000, v60
	v_pk_fma_f32 v[58:59], v[66:67], v[54:55], v[58:59] op_sel:[0,1,0] op_sel_hi:[1,0,1]
	s_nop 0
	v_pk_fma_f32 v[54:55], v[64:65], v[54:55], v[58:59]
	v_lshlrev_b32_e32 v58, 16, v61
	v_and_b32_e32 v59, 0xffff0000, v61
	v_pk_fma_f32 v[58:59], v[66:67], v[54:55], v[58:59] op_sel:[0,1,0] op_sel_hi:[1,0,1]
	s_nop 0
	v_pk_fma_f32 v[54:55], v[64:65], v[54:55], v[58:59]
	s_waitcnt lgkmcnt(0)
	v_lshlrev_b32_e32 v58, 16, v56
	v_and_b32_e32 v59, 0xffff0000, v56
	v_pk_fma_f32 v[58:59], v[66:67], v[54:55], v[58:59] op_sel:[0,1,0] op_sel_hi:[1,0,1]
	v_lshlrev_b32_e32 v56, 16, v57
	v_pk_fma_f32 v[54:55], v[64:65], v[54:55], v[58:59]
	v_and_b32_e32 v57, 0xffff0000, v57
	v_pk_fma_f32 v[56:57], v[66:67], v[54:55], v[56:57] op_sel:[0,1,0] op_sel_hi:[1,0,1]
	s_nop 0
	v_pk_fma_f32 v[68:69], v[64:65], v[54:55], v[56:57]
	s_cbranch_scc0 .LBB0_665

; #define LAS __attribute__((address_space(3)))
; __device__ __forceinline__ unsigned pk2n(float lo, float hi) { const f32x2 v = {lo, hi}; const bf16x2n b = __builtin_convertvector(v, bf16x2n); return __builtin_bit_cast(unsigned, b); }
; __device__ __forceinline__ float bflo(unsigned w) { return __uint_as_float(w << 16); }
; __device__ __forceinline__ float bfhi(unsigned w) { return __uint_as_float(w & 0xffff0000u); }
; #define CFENCE() asm volatile("" ::: "memory")
; template <bool OUT> ...
;     ...
;         u32x2 bwp[2][8];
; #pragma unroll
;         for (int mt = 0; mt < 2; ++mt)
; #pragma unroll
;             for (int nt = 0; nt < 8; ++nt) {
;                 const f32x4 bu = __builtin_amdgcn_mfma_f32_16x16x32_bf16(bfrag[nt], ua[mt], (f32x4){0.f, 0.f, 0.f, 0.f}, 0, 0, 0);
;                 bwp[mt][nt].x = pk2n(bu.x, bu.y); bwp[mt][nt].y = pk2n(bu.z, bu.w);
;             }
;         __builtin_amdgcn_sched_barrier(0);
; #pragma unroll
;         for (int mt = 0; mt < 2; ++mt)
; #pragma unroll
;             for (int nt = 0; nt < 8; ++nt) *(LAS u32x2*)(wl + (16 * mt + fr) * 68 + 8 * nt + 2 * fq) = bwp[mt][nt];
;         DS_GUARD();
;         CFENCE();
;         {
;             f32x2 hv = {hr, hi}; const f32x2 L1 = {lr, lr}, L2 = {-li, li};
;             unsigned cur8[8], nxt8[8], hw8[8];
; #pragma unroll
;             for (int j = 0; j < 8; ++j) cur8[j] = wl[j * 68 + lane];
; #pragma unroll
;             for (int blk = 0; blk < 4; ++blk) {
;                 if (blk < 3) {
; #pragma unroll
;                     for (int j = 0; j < 8; ++j) nxt8[j] = wl[(8 * (blk + 1) + j) * 68 + lane];
;                 }
; #pragma unroll
;                 for (int j = 0; j < 8; ++j) {
;                     const unsigned bw = cur8[j];
;                     const f32x2 bv = {bflo(bw), bfhi(bw)};
;                     const f32x2 hs = __builtin_shufflevector(hv, hv, 1, 0);
;                     hv = __builtin_elementwise_fma(L1, hv, __builtin_elementwise_fma(L2, hs, bv));
;                     if (OUT) hw8[j] = pk2n(hv.x, hv.y);
;                 }
;                 if (OUT) {
;                     __builtin_amdgcn_sched_barrier(0);
; #pragma unroll
;                     for (int j = 0; j < 8; ++j) wl[(8 * blk + j) * 68 + lane] = hw8[j];
;                     DS_GUARD();
.LBB0_671:
	s_or_b64 exec, exec, s[12:13]
	s_waitcnt lgkmcnt(1)
	v_mfma_f32_16x16x32_bf16 v[146:149], v[6:9], v[58:61], 0
	v_add_u32_e32 v68, 0x12200, v69
	ds_read_b64 v[68:69], v68
	v_mfma_f32_16x16x32_bf16 v[150:153], v[14:17], v[58:61], 0
	v_mfma_f32_16x16x32_bf16 v[154:157], v[2:5], v[58:61], 0
	v_mfma_f32_16x16x32_bf16 v[158:161], v[10:13], v[58:61], 0
	v_mfma_f32_16x16x32_bf16 v[162:165], v[18:21], v[58:61], 0
	v_mfma_f32_16x16x32_bf16 v[166:169], v[22:25], v[58:61], 0
	v_mfma_f32_16x16x32_bf16 v[170:173], v[26:29], v[58:61], 0
	v_mfma_f32_16x16x32_bf16 v[174:177], v[30:33], v[58:61], 0
	s_waitcnt lgkmcnt(1)
	v_mfma_f32_16x16x32_bf16 v[178:181], v[6:9], v[54:57], 0
	v_mfma_f32_16x16x32_bf16 v[182:185], v[2:5], v[54:57], 0
	v_mfma_f32_16x16x32_bf16 v[186:189], v[10:13], v[54:57], 0
	v_mfma_f32_16x16x32_bf16 v[190:193], v[14:17], v[54:57], 0
	v_mfma_f32_16x16x32_bf16 v[194:197], v[18:21], v[54:57], 0
	v_mfma_f32_16x16x32_bf16 v[198:201], v[22:25], v[54:57], 0
	v_mfma_f32_16x16x32_bf16 v[202:205], v[26:29], v[54:57], 0
	v_mfma_f32_16x16x32_bf16 v[206:209], v[30:33], v[54:57], 0
	v_cvt_pk_bf16_f32 v74, v146, v147
	v_cvt_pk_bf16_f32 v75, v148, v149
	v_cvt_pk_bf16_f32 v76, v154, v155
	v_cvt_pk_bf16_f32 v77, v156, v157
	v_cvt_pk_bf16_f32 v78, v158, v159
	v_cvt_pk_bf16_f32 v79, v160, v161
	v_cvt_pk_bf16_f32 v80, v150, v151
	v_cvt_pk_bf16_f32 v81, v152, v153
	v_cvt_pk_bf16_f32 v104, v162, v163
	v_cvt_pk_bf16_f32 v105, v164, v165
	v_cvt_pk_bf16_f32 v106, v166, v167
	v_cvt_pk_bf16_f32 v107, v168, v169
	v_cvt_pk_bf16_f32 v100, v170, v171
	v_cvt_pk_bf16_f32 v101, v172, v173
	v_cvt_pk_bf16_f32 v102, v174, v175
	v_cvt_pk_bf16_f32 v103, v176, v177
	v_cvt_pk_bf16_f32 v108, v178, v179
	v_cvt_pk_bf16_f32 v109, v180, v181
	v_cvt_pk_bf16_f32 v110, v182, v183
	v_cvt_pk_bf16_f32 v111, v184, v185
	v_cvt_pk_bf16_f32 v112, v186, v187
	v_cvt_pk_bf16_f32 v113, v188, v189
	v_cvt_pk_bf16_f32 v114, v190, v191
	v_cvt_pk_bf16_f32 v115, v192, v193
	v_cvt_pk_bf16_f32 v116, v194, v195
	v_cvt_pk_bf16_f32 v117, v196, v197
	v_cvt_pk_bf16_f32 v118, v198, v199
	v_cvt_pk_bf16_f32 v119, v200, v201
	v_cvt_pk_bf16_f32 v58, v202, v203
	v_cvt_pk_bf16_f32 v59, v204, v205
	v_cvt_pk_bf16_f32 v54, v206, v207
	v_cvt_pk_bf16_f32 v55, v208, v209
	ds_write2_b64 v85, v[74:75], v[76:77] offset1:4
	ds_write2_b64 v85, v[78:79], v[80:81] offset0:8 offset1:12
	ds_write2_b64 v85, v[104:105], v[106:107] offset0:16 offset1:20
	ds_write2_b64 v85, v[100:101], v[102:103] offset0:24 offset1:28
	ds_write2_b64 v86, v[108:109], v[110:111] offset0:32 offset1:36
	ds_write2_b64 v86, v[112:113], v[114:115] offset0:40 offset1:44
	ds_write2_b64 v86, v[116:117], v[118:119] offset0:48 offset1:52
	ds_write2_b64 v86, v[58:59], v[54:55] offset0:56 offset1:60
	s_waitcnt lgkmcnt(0)
	ds_read2_b32 v[54:55], v83 offset1:68
	ds_read2_b32 v[56:57], v83 offset0:136 offset1:204
	ds_read2_b32 v[58:59], v87 offset0:16 offset1:84
	ds_read2_b32 v[60:61], v87 offset0:152 offset1:220
	ds_read2_b32 v[74:75], v88 offset0:32 offset1:100
	ds_read2_b32 v[76:77], v88 offset0:168 offset1:236
	ds_read2_b32 v[78:79], v89 offset0:48 offset1:116
	ds_read2_b32 v[80:81], v89 offset0:184 offset1:252
	s_waitcnt lgkmcnt(7)
	v_lshlrev_b32_e32 v100, 16, v54
	v_and_b32_e32 v101, 0xffff0000, v54
	v_pk_fma_f32 v[100:101], v[66:67], v[72:73], v[100:101] op_sel:[0,1,0] op_sel_hi:[1,0,1]
	v_lshlrev_b32_e32 v54, 16, v55
	v_pk_fma_f32 v[72:73], v[64:65], v[72:73], v[100:101]
	v_and_b32_e32 v55, 0xffff0000, v55
	v_pk_fma_f32 v[54:55], v[66:67], v[72:73], v[54:55] op_sel:[0,1,0] op_sel_hi:[1,0,1]
	v_cvt_pk_bf16_f32 v99, v72, v73
	v_pk_fma_f32 v[54:55], v[64:65], v[72:73], v[54:55]
	s_waitcnt lgkmcnt(6)
	v_lshlrev_b32_e32 v72, 16, v56
	v_and_b32_e32 v73, 0xffff0000, v56
	v_pk_fma_f32 v[72:73], v[66:67], v[54:55], v[72:73] op_sel:[0,1,0] op_sel_hi:[1,0,1]
	v_cvt_pk_bf16_f32 v100, v54, v55
	v_pk_fma_f32 v[54:55], v[64:65], v[54:55], v[72:73]
	v_lshlrev_b32_e32 v56, 16, v57
	v_and_b32_e32 v57, 0xffff0000, v57
	v_pk_fma_f32 v[56:57], v[66:67], v[54:55], v[56:57] op_sel:[0,1,0] op_sel_hi:[1,0,1]
	v_cvt_pk_bf16_f32 v72, v54, v55
	v_pk_fma_f32 v[54:55], v[64:65], v[54:55], v[56:57]
	s_waitcnt lgkmcnt(5)
	v_lshlrev_b32_e32 v56, 16, v58
	v_and_b32_e32 v57, 0xffff0000, v58
	v_pk_fma_f32 v[56:57], v[66:67], v[54:55], v[56:57] op_sel:[0,1,0] op_sel_hi:[1,0,1]
	v_cvt_pk_bf16_f32 v73, v54, v55
	v_pk_fma_f32 v[54:55], v[64:65], v[54:55], v[56:57]
	v_lshlrev_b32_e32 v56, 16, v59
	v_and_b32_e32 v57, 0xffff0000, v59
	v_pk_fma_f32 v[56:57], v[66:67], v[54:55], v[56:57] op_sel:[0,1,0] op_sel_hi:[1,0,1]
	v_cvt_pk_bf16_f32 v58, v54, v55
	v_pk_fma_f32 v[54:55], v[64:65], v[54:55], v[56:57]
	s_waitcnt lgkmcnt(4)
	v_lshlrev_b32_e32 v56, 16, v60
	v_and_b32_e32 v57, 0xffff0000, v60
	v_pk_fma_f32 v[56:57], v[66:67], v[54:55], v[56:57] op_sel:[0,1,0] op_sel_hi:[1,0,1]
	v_cvt_pk_bf16_f32 v59, v54, v55
	v_pk_fma_f32 v[54:55], v[64:65], v[54:55], v[56:57]
	v_lshlrev_b32_e32 v56, 16, v61
	v_and_b32_e32 v57, 0xffff0000, v61
	v_pk_fma_f32 v[56:57], v[66:67], v[54:55], v[56:57] op_sel:[0,1,0] op_sel_hi:[1,0,1]
	v_cvt_pk_bf16_f32 v60, v54, v55
	v_pk_fma_f32 v[54:55], v[64:65], v[54:55], v[56:57]
	s_nop 0
	v_cvt_pk_bf16_f32 v56, v54, v55
	ds_write2_b32 v83, v99, v100 offset1:68
	ds_write2_b32 v83, v72, v73 offset0:136 offset1:204
	ds_write2_b32 v87, v58, v59 offset0:16 offset1:84
	ds_write2_b32 v87, v60, v56 offset0:152 offset1:220
	s_waitcnt lgkmcnt(0)
	s_waitcnt lgkmcnt(7)
; __device__ __forceinline__ unsigned pk2n(float lo, float hi) { const f32x2 v = {lo, hi}; const bf16x2n b = __builtin_convertvector(v, bf16x2n); return __builtin_bit_cast(unsigned, b); }
; __device__ __forceinline__ float bflo(unsigned w) { return __uint_as_float(w << 16); }
; __device__ __forceinline__ float bfhi(unsigned w) { return __uint_as_float(w & 0xffff0000u); }
; #define DS_GUARD() do { __builtin_amdgcn_sched_barrier(0); asm volatile("s_waitcnt lgkmcnt(0)" ::: "memory"); __builtin_amdgcn_sched_barrier(0); } while (0)
; template <bool OUT> ...
;     ...
;             for (int blk = 0; blk < 4; ++blk) {
;                 if (blk < 3) {
; #pragma unroll
;                     for (int j = 0; j < 8; ++j) nxt8[j] = wl[(8 * (blk + 1) + j) * 68 + lane];
;                 }
; #pragma unroll
;                 for (int j = 0; j < 8; ++j) {
;                     const unsigned bw = cur8[j];
;                     const f32x2 bv = {bflo(bw), bfhi(bw)};
;                     const f32x2 hs = __builtin_shufflevector(hv, hv, 1, 0);
;                     hv = __builtin_elementwise_fma(L1, hv, __builtin_elementwise_fma(L2, hs, bv));
;                     if (OUT) hw8[j] = pk2n(hv.x, hv.y);
;                 }
;                 if (OUT) {
;                     __builtin_amdgcn_sched_barrier(0);
; #pragma unroll
;                     for (int j = 0; j < 8; ++j) wl[(8 * blk + j) * 68 + lane] = hw8[j];
;                     DS_GUARD();
;                 }
; #pragma unroll
;                 for (int j = 0; j < 8; ++j) cur8[j] = nxt8[j];
	v_lshlrev_b32_e32 v100, 16, v74
	v_and_b32_e32 v101, 0xffff0000, v74
	v_pk_fma_f32 v[100:101], v[66:67], v[54:55], v[100:101] op_sel:[0,1,0] op_sel_hi:[1,0,1]
	v_lshlrev_b32_e32 v74, 16, v75
	v_pk_fma_f32 v[54:55], v[64:65], v[54:55], v[100:101]
	v_and_b32_e32 v75, 0xffff0000, v75
	v_pk_fma_f32 v[74:75], v[66:67], v[54:55], v[74:75] op_sel:[0,1,0] op_sel_hi:[1,0,1]
	v_cvt_pk_bf16_f32 v99, v54, v55
	v_pk_fma_f32 v[54:55], v[64:65], v[54:55], v[74:75]
	s_waitcnt lgkmcnt(6)
	v_lshlrev_b32_e32 v74, 16, v76
	v_and_b32_e32 v75, 0xffff0000, v76
	v_pk_fma_f32 v[74:75], v[66:67], v[54:55], v[74:75] op_sel:[0,1,0] op_sel_hi:[1,0,1]
	v_cvt_pk_bf16_f32 v100, v54, v55
	v_pk_fma_f32 v[54:55], v[64:65], v[54:55], v[74:75]
	v_lshlrev_b32_e32 v74, 16, v77
	v_and_b32_e32 v75, 0xffff0000, v77
	v_pk_fma_f32 v[74:75], v[66:67], v[54:55], v[74:75] op_sel:[0,1,0] op_sel_hi:[1,0,1]
	v_cvt_pk_bf16_f32 v76, v54, v55
	v_pk_fma_f32 v[54:55], v[64:65], v[54:55], v[74:75]
	s_waitcnt lgkmcnt(5)
	v_lshlrev_b32_e32 v74, 16, v78
	v_and_b32_e32 v75, 0xffff0000, v78
	v_pk_fma_f32 v[74:75], v[66:67], v[54:55], v[74:75] op_sel:[0,1,0] op_sel_hi:[1,0,1]
	ds_read2_b32 v[56:57], v90 offset0:64 offset1:132
	ds_read2_b32 v[58:59], v91 offset0:72 offset1:140
	ds_read2_b32 v[60:61], v92 offset0:80 offset1:148
	ds_read2_b32 v[72:73], v93 offset0:88 offset1:156
	v_cvt_pk_bf16_f32 v77, v54, v55
	v_pk_fma_f32 v[54:55], v[64:65], v[54:55], v[74:75]
	v_lshlrev_b32_e32 v74, 16, v79
	v_and_b32_e32 v75, 0xffff0000, v79
	v_pk_fma_f32 v[74:75], v[66:67], v[54:55], v[74:75] op_sel:[0,1,0] op_sel_hi:[1,0,1]
	v_cvt_pk_bf16_f32 v78, v54, v55
	v_pk_fma_f32 v[54:55], v[64:65], v[54:55], v[74:75]
	s_waitcnt lgkmcnt(8)
	v_lshlrev_b32_e32 v74, 16, v80
	v_and_b32_e32 v75, 0xffff0000, v80
	v_pk_fma_f32 v[74:75], v[66:67], v[54:55], v[74:75] op_sel:[0,1,0] op_sel_hi:[1,0,1]
	v_cvt_pk_bf16_f32 v79, v54, v55
	v_pk_fma_f32 v[54:55], v[64:65], v[54:55], v[74:75]
	v_lshlrev_b32_e32 v74, 16, v81
	v_and_b32_e32 v75, 0xffff0000, v81
	v_pk_fma_f32 v[74:75], v[66:67], v[54:55], v[74:75] op_sel:[0,1,0] op_sel_hi:[1,0,1]
	v_cvt_pk_bf16_f32 v80, v54, v55
	v_pk_fma_f32 v[54:55], v[64:65], v[54:55], v[74:75]
	s_nop 0
	v_cvt_pk_bf16_f32 v74, v54, v55
	ds_write2_b32 v88, v99, v100 offset0:32 offset1:100
	ds_write2_b32 v88, v76, v77 offset0:168 offset1:236
	ds_write2_b32 v89, v78, v79 offset0:48 offset1:116
	ds_write2_b32 v89, v80, v74 offset0:184 offset1:252
	s_waitcnt lgkmcnt(0)
	s_waitcnt lgkmcnt(7)
	v_lshlrev_b32_e32 v100, 16, v56
	v_and_b32_e32 v101, 0xffff0000, v56
	v_pk_fma_f32 v[100:101], v[66:67], v[54:55], v[100:101] op_sel:[0,1,0] op_sel_hi:[1,0,1]
	v_lshlrev_b32_e32 v56, 16, v57
	v_pk_fma_f32 v[54:55], v[64:65], v[54:55], v[100:101]
	v_and_b32_e32 v57, 0xffff0000, v57
	v_pk_fma_f32 v[56:57], v[66:67], v[54:55], v[56:57] op_sel:[0,1,0] op_sel_hi:[1,0,1]
	v_cvt_pk_bf16_f32 v99, v54, v55
	v_pk_fma_f32 v[54:55], v[64:65], v[54:55], v[56:57]
	s_waitcnt lgkmcnt(6)
	v_lshlrev_b32_e32 v56, 16, v58
	v_and_b32_e32 v57, 0xffff0000, v58
	v_pk_fma_f32 v[56:57], v[66:67], v[54:55], v[56:57] op_sel:[0,1,0] op_sel_hi:[1,0,1]
	v_cvt_pk_bf16_f32 v100, v54, v55
	v_pk_fma_f32 v[54:55], v[64:65], v[54:55], v[56:57]
	v_lshlrev_b32_e32 v56, 16, v59
	v_and_b32_e32 v57, 0xffff0000, v59
	v_pk_fma_f32 v[56:57], v[66:67], v[54:55], v[56:57] op_sel:[0,1,0] op_sel_hi:[1,0,1]
	v_cvt_pk_bf16_f32 v58, v54, v55
	v_pk_fma_f32 v[54:55], v[64:65], v[54:55], v[56:57]
	s_waitcnt lgkmcnt(5)
	v_lshlrev_b32_e32 v56, 16, v60
	v_and_b32_e32 v57, 0xffff0000, v60
	v_pk_fma_f32 v[56:57], v[66:67], v[54:55], v[56:57] op_sel:[0,1,0] op_sel_hi:[1,0,1]
	ds_read2_b32 v[74:75], v95 offset0:96 offset1:164
	ds_read2_b32 v[76:77], v97 offset0:104 offset1:172
	ds_read2_b32 v[78:79], v96 offset0:112 offset1:180
	ds_read2_b32 v[80:81], v94 offset0:120 offset1:188
	v_cvt_pk_bf16_f32 v59, v54, v55
	v_pk_fma_f32 v[54:55], v[64:65], v[54:55], v[56:57]
	v_lshlrev_b32_e32 v56, 16, v61
	v_and_b32_e32 v57, 0xffff0000, v61
	v_pk_fma_f32 v[56:57], v[66:67], v[54:55], v[56:57] op_sel:[0,1,0] op_sel_hi:[1,0,1]
	v_cvt_pk_bf16_f32 v60, v54, v55
	v_pk_fma_f32 v[54:55], v[64:65], v[54:55], v[56:57]
	s_waitcnt lgkmcnt(8)
	v_lshlrev_b32_e32 v56, 16, v72
	v_and_b32_e32 v57, 0xffff0000, v72
	v_pk_fma_f32 v[56:57], v[66:67], v[54:55], v[56:57] op_sel:[0,1,0] op_sel_hi:[1,0,1]
	v_cvt_pk_bf16_f32 v61, v54, v55
	v_pk_fma_f32 v[54:55], v[64:65], v[54:55], v[56:57]
	v_lshlrev_b32_e32 v56, 16, v73
	v_and_b32_e32 v57, 0xffff0000, v73
	v_pk_fma_f32 v[56:57], v[66:67], v[54:55], v[56:57] op_sel:[0,1,0] op_sel_hi:[1,0,1]
	v_cvt_pk_bf16_f32 v72, v54, v55
	v_pk_fma_f32 v[54:55], v[64:65], v[54:55], v[56:57]
	s_nop 0
	v_cvt_pk_bf16_f32 v56, v54, v55
	ds_write2_b32 v90, v99, v100 offset0:64 offset1:132
	ds_write2_b32 v91, v58, v59 offset0:72 offset1:140
	ds_write2_b32 v92, v60, v61 offset0:80 offset1:148
	ds_write2_b32 v93, v72, v56 offset0:88 offset1:156
	s_waitcnt lgkmcnt(0)
	s_waitcnt lgkmcnt(7)
	v_lshlrev_b32_e32 v56, 16, v74
	v_and_b32_e32 v57, 0xffff0000, v74
	v_pk_fma_f32 v[56:57], v[66:67], v[54:55], v[56:57] op_sel:[0,1,0] op_sel_hi:[1,0,1]
	s_nop 0
	v_pk_fma_f32 v[54:55], v[64:65], v[54:55], v[56:57]
	v_lshlrev_b32_e32 v56, 16, v75
	v_and_b32_e32 v57, 0xffff0000, v75
	v_pk_fma_f32 v[56:57], v[66:67], v[54:55], v[56:57] op_sel:[0,1,0] op_sel_hi:[1,0,1]
	v_cvt_pk_bf16_f32 v58, v54, v55
	v_pk_fma_f32 v[54:55], v[64:65], v[54:55], v[56:57]
	s_waitcnt lgkmcnt(6)
; #define LAS __attribute__((address_space(3)))
; __device__ __forceinline__ unsigned pk2n(float lo, float hi) { const f32x2 v = {lo, hi}; const bf16x2n b = __builtin_convertvector(v, bf16x2n); return __builtin_bit_cast(unsigned, b); }
; __device__ __forceinline__ float bflo(unsigned w) { return __uint_as_float(w << 16); }
; __device__ __forceinline__ float bfhi(unsigned w) { return __uint_as_float(w & 0xffff0000u); }
; __device__ __forceinline__ float gelu_tanh(float x) { const float u = 0.7978845608028654f * (x + 0.044715f * x * x * x); return x * sigmoidf_(2.0f * u); }
; #define CFENCE() asm volatile("" ::: "memory")
; #define DS_GUARD() do { __builtin_amdgcn_sched_barrier(0); asm volatile("s_waitcnt lgkmcnt(0)" ::: "memory"); __builtin_amdgcn_sched_barrier(0); } while (0)
; template <bool OUT> ...
;     ...
;                 if (OUT) {
;                     __builtin_amdgcn_sched_barrier(0);
; #pragma unroll
;                     for (int j = 0; j < 8; ++j) wl[(8 * blk + j) * 68 + lane] = hw8[j];
;                     DS_GUARD();
;                 }
; #pragma unroll
;                 for (int j = 0; j < 8; ++j) cur8[j] = nxt8[j];
;             }
;             hr = hv.x; hi = hv.y;
;         }
;         CFENCE();
;         if (OUT) {
;             f32x4 y[2]; bf16x8 hf[2][4];
; #pragma unroll
;             for (int mt = 0; mt < 2; ++mt)
; #pragma unroll
;                 for (int ks = 0; ks < 4; ++ks) hf[mt][ks] = *(const LAS bf16x8*)((const LAS char*)wl + (16 * mt + fr) * 272 + 64 * ks + 16 * fq);
;             y[0] = (f32x4){0.f, 0.f, 0.f, 0.f}; y[1] = y[0];
; #pragma unroll
;             for (int ks = 0; ks < 4; ++ks)
; #pragma unroll
;                 for (int mt = 0; mt < 2; ++mt) y[mt] = __builtin_amdgcn_mfma_f32_16x16x32_bf16(cfrag[ks], hf[mt][ks], y[mt], 0, 0, 0);
; #pragma unroll
;             for (int mt = 0; mt < 2; ++mt) {
;                 const size_t row = r0 + 16 * mt + fr;
;                 const float v0 = y[mt].x + Dv.x * bflo(uw[mt].x), v1 = y[mt].y + Dv.y * bfhi(uw[mt].x), v2 = y[mt].z + Dv.z * bflo(uw[mt].y), v3 = y[mt].w + Dv.w * bfhi(uw[mt].y);
;                 u32x2 o; o.x = pk2n(gelu_tanh(v0), gelu_tanh(v1)); o.y = pk2n(gelu_tanh(v2), gelu_tanh(v3));
;                 *(u32x2*)(zg + ((size_t)g * M + row) * 16 + 4 * fq) = o;
;             }
	v_lshlrev_b32_e32 v56, 16, v76
	v_and_b32_e32 v57, 0xffff0000, v76
	v_pk_fma_f32 v[56:57], v[66:67], v[54:55], v[56:57] op_sel:[0,1,0] op_sel_hi:[1,0,1]
	v_cvt_pk_bf16_f32 v59, v54, v55
	v_pk_fma_f32 v[54:55], v[64:65], v[54:55], v[56:57]
	v_lshlrev_b32_e32 v56, 16, v77
	v_and_b32_e32 v57, 0xffff0000, v77
	v_pk_fma_f32 v[56:57], v[66:67], v[54:55], v[56:57] op_sel:[0,1,0] op_sel_hi:[1,0,1]
	v_cvt_pk_bf16_f32 v60, v54, v55
	v_pk_fma_f32 v[54:55], v[64:65], v[54:55], v[56:57]
	s_waitcnt lgkmcnt(5)
	v_lshlrev_b32_e32 v56, 16, v78
	v_and_b32_e32 v57, 0xffff0000, v78
	v_pk_fma_f32 v[56:57], v[66:67], v[54:55], v[56:57] op_sel:[0,1,0] op_sel_hi:[1,0,1]
	v_cvt_pk_bf16_f32 v61, v54, v55
	v_pk_fma_f32 v[54:55], v[64:65], v[54:55], v[56:57]
	v_lshlrev_b32_e32 v56, 16, v79
	v_and_b32_e32 v57, 0xffff0000, v79
	v_pk_fma_f32 v[56:57], v[66:67], v[54:55], v[56:57] op_sel:[0,1,0] op_sel_hi:[1,0,1]
	v_cvt_pk_bf16_f32 v74, v54, v55
	v_pk_fma_f32 v[54:55], v[64:65], v[54:55], v[56:57]
	s_waitcnt lgkmcnt(4)
	v_lshlrev_b32_e32 v56, 16, v80
	v_and_b32_e32 v57, 0xffff0000, v80
	v_pk_fma_f32 v[56:57], v[66:67], v[54:55], v[56:57] op_sel:[0,1,0] op_sel_hi:[1,0,1]
	v_cvt_pk_bf16_f32 v75, v54, v55
	v_pk_fma_f32 v[54:55], v[64:65], v[54:55], v[56:57]
	v_lshlrev_b32_e32 v56, 16, v81
	v_and_b32_e32 v57, 0xffff0000, v81
	v_pk_fma_f32 v[56:57], v[66:67], v[54:55], v[56:57] op_sel:[0,1,0] op_sel_hi:[1,0,1]
	v_cvt_pk_bf16_f32 v76, v54, v55
	v_pk_fma_f32 v[72:73], v[64:65], v[54:55], v[56:57]
	s_nop 0
	v_cvt_pk_bf16_f32 v54, v72, v73
	ds_write2_b32 v95, v58, v59 offset0:96 offset1:164
	ds_write2_b32 v97, v60, v61 offset0:104 offset1:172
	ds_write2_b32 v96, v74, v75 offset0:112 offset1:180
	ds_write2_b32 v94, v76, v54 offset0:120 offset1:188
	s_waitcnt lgkmcnt(0)
	ds_read_b128 v[54:57], v98
	ds_read_b128 v[74:77], v98 offset:64
	ds_read_b128 v[58:61], v98 offset:4352
	v_lshlrev_b32_e32 v104, 16, v70
	v_and_b32_e32 v105, 0xffff0000, v70
	s_waitcnt lgkmcnt(2)
	v_mfma_f32_16x16x32_bf16 v[54:57], v[34:37], v[54:57], 0
	s_addk_i32 s24, 0x400
	s_mov_b64 s[12:13], 0x400
	s_cmpk_lg_i32 s24, 0x2000
	s_waitcnt lgkmcnt(1)
	v_mfma_f32_16x16x32_bf16 v[54:57], v[38:41], v[74:77], v[54:57]
	ds_read_b128 v[74:77], v98 offset:128
	ds_read_b128 v[78:81], v98 offset:192
	s_waitcnt lgkmcnt(1)
	v_mfma_f32_16x16x32_bf16 v[54:57], v[42:45], v[74:77], v[54:57]
	ds_read_b128 v[74:77], v98 offset:4416
	s_waitcnt lgkmcnt(1)
	v_mfma_f32_16x16x32_bf16 v[54:57], v[46:49], v[78:81], v[54:57]
	ds_read_b128 v[78:81], v98 offset:4480
	ds_read_b128 v[100:103], v98 offset:4544
	v_mfma_f32_16x16x32_bf16 v[58:61], v[34:37], v[58:61], 0
	s_nop 4
	v_fma_f32 v104, v50, v104, v54
	v_fma_f32 v105, v51, v105, v55
	v_mul_f32_e32 v54, 0x3d372713, v104
	v_mul_f32_e32 v55, 0x3d372713, v105
	v_mul_f32_e32 v54, v104, v54
	v_mul_f32_e32 v55, v105, v55
	v_fma_f32 v54, v104, v54, v104
	v_fma_f32 v55, v105, v55, v105
	v_mul_f32_e32 v54, 0x3f4c422a, v54
	v_mul_f32_e32 v55, 0x3f4c422a, v55
	v_add_f32_e32 v54, v54, v54
	v_add_f32_e32 v55, v55, v55
	v_mul_f32_e32 v54, 0xbfb8aa3b, v54
	v_exp_f32_e32 v54, v54
	v_mul_f32_e32 v55, 0xbfb8aa3b, v55
	v_exp_f32_e32 v55, v55
	s_waitcnt lgkmcnt(2)
	v_mfma_f32_16x16x32_bf16 v[58:61], v[38:41], v[74:77], v[58:61]
	v_add_f32_e32 v54, 1.0, v54
	v_rcp_f32_e32 v70, v54
	v_add_f32_e32 v76, 1.0, v55
	v_lshlrev_b32_e32 v54, 16, v71
	v_and_b32_e32 v55, 0xffff0000, v71
	v_pk_fma_f32 v[74:75], v[52:53], v[54:55], v[56:57]
	s_waitcnt lgkmcnt(1)
	v_mfma_f32_16x16x32_bf16 v[58:61], v[42:45], v[78:81], v[58:61]
	v_mul_f32_e32 v54, 0x3d372713, v74
	v_mul_f32_e32 v54, v74, v54
	v_mul_f32_e32 v55, 0x3d372713, v75
	v_fma_f32 v54, v74, v54, v74
	v_mul_f32_e32 v55, v75, v55
	v_mul_f32_e32 v54, 0x3f4c422a, v54
	v_fma_f32 v55, v75, v55, v75
	v_add_f32_e32 v54, v54, v54
	v_mul_f32_e32 v55, 0x3f4c422a, v55
	v_mul_f32_e32 v54, 0xbfb8aa3b, v54
	v_add_f32_e32 v55, v55, v55
	v_exp_f32_e32 v54, v54
	v_mul_f32_e32 v55, 0xbfb8aa3b, v55
	v_exp_f32_e32 v55, v55
	v_rcp_f32_e32 v71, v76
	v_add_f32_e32 v54, 1.0, v54
	v_rcp_f32_e32 v76, v54
	v_add_f32_e32 v54, 1.0, v55
	v_rcp_f32_e32 v77, v54
	s_waitcnt lgkmcnt(0)
	v_mfma_f32_16x16x32_bf16 v[54:57], v[46:49], v[100:103], v[58:61]
	s_nop 2
	v_mul_f32_e64 v58, v104, v70
	v_mul_f32_e64 v59, v105, v71
	v_lshlrev_b32_e32 v70, 16, v68
	v_and_b32_e32 v71, 0xffff0000, v68
	s_nop 0
	v_pk_fma_f32 v[54:55], v[50:51], v[70:71], v[54:55]
	v_cvt_pk_bf16_f32 v58, v58, v59
	v_mul_f32_e32 v59, 0x3d372713, v54
	v_mul_f32_e32 v59, v54, v59
	v_fma_f32 v59, v54, v59, v54
	v_mul_f32_e32 v59, 0x3f4c422a, v59
	v_add_f32_e32 v59, v59, v59
	v_mul_f32_e32 v59, 0xbfb8aa3b, v59
	v_exp_f32_e32 v68, v59
	v_mul_f32_e32 v59, 0x3d372713, v55
	v_mul_f32_e32 v59, v55, v59
	v_fma_f32 v59, v55, v59, v55
	v_mul_f32_e32 v59, 0x3f4c422a, v59
	v_add_f32_e32 v59, v59, v59
	v_pk_mul_f32 v[60:61], v[74:75], v[76:77]
	v_mul_f32_e32 v59, 0xbfb8aa3b, v59
	v_exp_f32_e32 v70, v59
	v_cvt_pk_bf16_f32 v59, v60, v61
	v_add_f32_e32 v60, 1.0, v68
	v_lshlrev_b32_e32 v68, 16, v69
	v_and_b32_e32 v69, 0xffff0000, v69
	v_pk_fma_f32 v[56:57], v[52:53], v[68:69], v[56:57]
	v_add_f32_e32 v61, 1.0, v70
	v_mul_f32_e32 v68, 0x3d372713, v56
	v_mul_f32_e32 v69, 0x3d372713, v57
	v_mul_f32_e32 v68, v56, v68
	v_mul_f32_e32 v69, v57, v69
	v_fma_f32 v68, v56, v68, v56
	v_fma_f32 v69, v57, v69, v57
	v_mul_f32_e32 v68, 0x3f4c422a, v68
	v_mul_f32_e32 v69, 0x3f4c422a, v69
	v_add_f32_e32 v68, v68, v68
	v_add_f32_e32 v69, v69, v69
	v_mul_f32_e32 v68, 0xbfb8aa3b, v68
	v_mul_f32_e32 v69, 0xbfb8aa3b, v69
	v_exp_f32_e32 v68, v68
	v_exp_f32_e32 v69, v69
	v_rcp_f32_e32 v60, v60
	v_rcp_f32_e32 v61, v61
	v_add_f32_e32 v68, 1.0, v68
	v_add_f32_e32 v69, 1.0, v69
	v_rcp_f32_e32 v68, v68
	v_rcp_f32_e32 v69, v69
	v_pk_mul_f32 v[54:55], v[54:55], v[60:61]
	global_store_dwordx2 v[62:63], v[58:59], off
	v_cvt_pk_bf16_f32 v54, v54, v55
	v_pk_mul_f32 v[56:57], v[56:57], v[68:69]
	s_nop 0
	v_cvt_pk_bf16_f32 v55, v56, v57
	global_store_dwordx2 v[62:63], v[54:55], off offset:512
	v_lshl_add_u64 v[62:63], v[62:63], 0, s[12:13]
	s_cbranch_scc0 .LBB0_640
